# natten dense tiles also accumulate in place; working set filled only on loop exit; bottom copy removed
# speedup vs baseline: 1.0115x; 1.0043x over previous
.LBB0_347:
	s_bitcmp1_b32 s85, 0
	s_cselect_b32 s3, 0x2c00, 0
	s_cmp_gt_i32 s85, s97
	s_mov_b64 s[86:87], -1
	s_cbranch_scc1 .LBB0_435
	v_add_u32_e32 v2, s85, v195
	v_cmp_ge_u32_e32 vcc, v2, v194
	v_cmp_lt_u32_e64 s[86:87], v2, v214
	v_mov_b32_e32 v221, v163
	v_mov_b32_e32 v166, v0
	v_mov_b32_e32 v222, v220
	v_mov_b32_e32 v162, v219
	s_and_b64 vcc, vcc, s[86:87]
	s_and_saveexec_b64 s[86:87], vcc
	s_cbranch_execz .LBB0_434
	v_lshl_add_u32 v162, s3, 1, v215
	ds_read_b128 v[2:5], v162
	ds_read_b128 v[22:25], v162 offset:32
	ds_read_b128 v[54:57], v192 offset:47104
	ds_read_b128 v[58:61], v192 offset:47136
	s_waitcnt lgkmcnt(3)
	v_mfma_f32_32x32x16_bf16 v[38:53], v[2:5], v[130:133], 0
	s_waitcnt lgkmcnt(1)
	v_mfma_f32_32x32x16_bf16 v[6:21], v[2:5], v[54:57], 0
	ds_read_b128 v[2:5], v162 offset:64
	ds_read_b128 v[62:65], v192 offset:47168
	v_mfma_f32_32x32x16_bf16 v[38:53], v[22:25], v[134:137], v[38:53]
	s_waitcnt lgkmcnt(2)
	v_mfma_f32_32x32x16_bf16 v[6:21], v[22:25], v[58:61], v[6:21]
	s_waitcnt lgkmcnt(1)
	v_mfma_f32_32x32x16_bf16 v[38:53], v[2:5], v[138:141], v[38:53]
	s_waitcnt lgkmcnt(0)
	v_mfma_f32_32x32x16_bf16 v[6:21], v[2:5], v[62:65], v[6:21]
	ds_read_b128 v[2:5], v162 offset:96
	ds_read_b128 v[164:167], v192 offset:47200
	s_waitcnt lgkmcnt(1)
	v_mfma_f32_32x32x16_bf16 v[38:53], v[2:5], v[142:145], v[38:53]
	s_waitcnt lgkmcnt(0)
	v_mfma_f32_32x32x16_bf16 v[6:21], v[2:5], v[164:167], v[6:21]
	ds_read_b128 v[2:5], v162 offset:4608
	s_waitcnt lgkmcnt(0)
	v_mfma_f32_32x32x16_bf16 v[22:37], v[2:5], v[130:133], 0
	v_mfma_f32_32x32x16_bf16 v[2:17], v[2:5], v[54:57], 0
	ds_read_b128 v[54:57], v162 offset:4640
	s_waitcnt lgkmcnt(0)
	v_mfma_f32_32x32x16_bf16 v[22:37], v[54:57], v[134:137], v[22:37]
	v_mfma_f32_32x32x16_bf16 v[2:17], v[54:57], v[58:61], v[2:17]
	ds_read_b128 v[54:57], v162 offset:4672
	s_waitcnt lgkmcnt(0)
	v_mfma_f32_32x32x16_bf16 v[22:37], v[54:57], v[138:141], v[22:37]
	v_mfma_f32_32x32x16_bf16 v[2:17], v[54:57], v[62:65], v[2:17]
	ds_read_b128 v[54:57], v162 offset:4704
	s_waitcnt lgkmcnt(0)
	v_mfma_f32_32x32x16_bf16 v[22:37], v[54:57], v[142:145], v[22:37]
	v_mfma_f32_32x32x16_bf16 v[2:17], v[54:57], v[164:167], v[2:17]
	s_nop 10
	v_mov_b32_e32 v35, 0xff800000
	ds_read2_b32 v[26:27], v218 offset0:9 offset1:8
	ds_read2_b32 v[28:29], v218 offset0:11 offset1:10
	ds_read2_b32 v[30:31], v218 offset0:17 offset1:16
	ds_read2_b32 v[32:33], v218 offset0:19 offset1:18
	ds_read_b32 v34, v218 offset:172
	ds_read_b32 v162, v218 offset:100
	ds_read_b32 v164, v218 offset:96
	ds_read_b32 v166, v218 offset:132
	ds_read_b32 v177, v218 offset:104
	ds_read2_b32 v[178:179], v218 offset0:27 offset1:32
	ds_read_b32 v181, v218 offset:136
	ds_read2_b32 v[182:183], v218 offset0:35 offset1:40
	ds_read2_b32 v[184:185], v218 offset0:41 offset1:42
	s_waitcnt lgkmcnt(0)
	v_add_f32_e32 v27, v38, v27
	v_add_f32_e32 v26, v39, v26
	v_add_f32_e32 v29, v40, v29
	v_add_f32_e32 v28, v41, v28
	v_add_f32_e32 v31, v42, v31
	v_add_f32_e32 v30, v43, v30
	v_add_f32_e32 v33, v44, v33
	v_add_f32_e32 v32, v45, v32
	v_add_f32_e32 v164, v46, v164
	v_add_f32_e32 v162, v47, v162
	v_add_f32_e32 v177, v48, v177
	v_add_f32_e32 v178, v49, v178
	v_add_f32_e32 v179, v50, v179
	v_add_f32_e32 v166, v51, v166
	v_add_f32_e32 v181, v52, v181
	v_add_f32_e32 v182, v53, v182
	v_add_f32_e32 v183, v22, v183
	v_add_f32_e32 v184, v23, v184
	v_add_f32_e32 v185, v24, v185
	v_add_f32_e32 v23, v25, v34
	v_cndmask_b32_e64 v27, v35, v27, s[0:1]
	v_cndmask_b32_e64 v26, v35, v26, s[4:5]
	v_cndmask_b32_e64 v29, v35, v29, s[6:7]
	v_cndmask_b32_e64 v28, v35, v28, s[8:9]
	v_cndmask_b32_e64 v31, v35, v31, s[10:11]
	v_cndmask_b32_e64 v30, v35, v30, s[12:13]
	v_cndmask_b32_e64 v33, v35, v33, s[14:15]
	v_cndmask_b32_e64 v32, v35, v32, s[16:17]
	v_cndmask_b32_e64 v164, v35, v164, s[18:19]
	v_cndmask_b32_e64 v162, v35, v162, s[20:21]
	v_cndmask_b32_e64 v177, v35, v177, s[22:23]
	v_cndmask_b32_e64 v178, v35, v178, s[24:25]
	v_cndmask_b32_e64 v179, v35, v179, s[26:27]
	v_cndmask_b32_e64 v166, v35, v166, s[28:29]
	v_cndmask_b32_e64 v181, v35, v181, s[30:31]
	v_cndmask_b32_e64 v182, v35, v182, s[34:35]
	v_cndmask_b32_e64 v183, v35, v183, s[36:37]
	v_cndmask_b32_e64 v184, v35, v184, s[38:39]
	v_cndmask_b32_e64 v185, v35, v185, s[40:41]
	v_cndmask_b32_e64 v23, v35, v23, s[42:43]
	v_and_b32_e32 v24, 64, v200
	v_xor_b32_e32 v22, 32, v200
	v_add_u32_e32 v24, 64, v24
	v_cmp_lt_i32_e32 vcc, v22, v24
	s_nop 1
	v_cndmask_b32_e32 v22, v200, v22, vcc
	v_lshlrev_b32_e32 v22, 2, v22
	v_max3_f32 v24, v27, v26, v29
	v_max3_f32 v24, v24, v28, v31
	v_max3_f32 v24, v24, v30, v33
	v_max3_f32 v24, v24, v32, v164
	v_max3_f32 v24, v24, v162, v177
	v_max3_f32 v24, v24, v178, v179
	v_max3_f32 v24, v24, v166, v181
	v_max3_f32 v24, v24, v182, v183
	v_max3_f32 v24, v24, v184, v185
	s_mov_b32 s88, 0xff800000
	v_max3_f32 v24, v24, v23, s88
	ds_bpermute_b32 v25, v22, v24
	s_waitcnt lgkmcnt(0)
	v_max_f32_e32 v25, v25, v25
	v_max_f32_e32 v24, v24, v25
	v_add_f32_e32 v25, 0xc1000000, v24
	v_cmp_gt_f32_e32 vcc, v25, v163
	v_mov_b32_e32 v165, v220
	v_mov_b32_e32 v221, v163
	s_cbranch_vccz .LBB0_391
	v_max_f32_e32 v24, v24, v24
	v_max_f32_e32 v25, v163, v163
	v_max_f32_e32 v221, v25, v24
	v_sub_f32_e32 v24, v163, v221
	v_exp_f32_e32 v24, v24
	s_nop 0
	v_mul_f32_e32 v165, v220, v24
	v_pk_mul_f32 v[128:129], v[128:129], v[24:25] op_sel_hi:[1,0]
	v_pk_mul_f32 v[126:127], v[126:127], v[24:25] op_sel_hi:[1,0]
	v_pk_mul_f32 v[124:125], v[124:125], v[24:25] op_sel_hi:[1,0]
	v_pk_mul_f32 v[122:123], v[122:123], v[24:25] op_sel_hi:[1,0]
	v_pk_mul_f32 v[120:121], v[120:121], v[24:25] op_sel_hi:[1,0]
	v_pk_mul_f32 v[118:119], v[118:119], v[24:25] op_sel_hi:[1,0]
	v_pk_mul_f32 v[116:117], v[116:117], v[24:25] op_sel_hi:[1,0]
	v_pk_mul_f32 v[114:115], v[114:115], v[24:25] op_sel_hi:[1,0]
	v_pk_mul_f32 v[112:113], v[112:113], v[24:25] op_sel_hi:[1,0]
	v_pk_mul_f32 v[110:111], v[110:111], v[24:25] op_sel_hi:[1,0]
	v_pk_mul_f32 v[108:109], v[108:109], v[24:25] op_sel_hi:[1,0]
	v_pk_mul_f32 v[106:107], v[106:107], v[24:25] op_sel_hi:[1,0]
	v_pk_mul_f32 v[104:105], v[104:105], v[24:25] op_sel_hi:[1,0]
	v_pk_mul_f32 v[102:103], v[102:103], v[24:25] op_sel_hi:[1,0]
	v_pk_mul_f32 v[100:101], v[100:101], v[24:25] op_sel_hi:[1,0]
	v_pk_mul_f32 v[98:99], v[98:99], v[24:25] op_sel_hi:[1,0]

.LBB0_433:
	v_add_f32_e32 v167, 0, v167
	v_add_f32_e32 v167, v168, v167
	v_add_f32_e32 v167, v169, v167
	v_add_f32_e32 v167, v170, v167
	v_add_f32_e32 v167, v171, v167
	v_add_f32_e32 v167, v172, v167
	v_add_f32_e32 v167, v173, v167
	v_add_f32_e32 v167, v174, v167
	v_add_f32_e32 v167, v175, v167
	v_add_f32_e32 v167, v176, v167
	v_add_f32_e32 v167, v177, v167
	v_add_f32_e32 v167, v178, v167
	v_add_f32_e32 v167, v179, v167
	v_add_f32_e32 v167, v180, v167
	v_add_f32_e32 v167, v181, v167
	v_add_f32_e32 v167, v182, v167
	v_add_f32_e32 v167, v183, v167
	v_add_f32_e32 v167, v184, v167
	v_add_f32_e32 v167, v185, v167
	v_add_f32_e32 v167, v186, v167
	v_sub_f32_e32 v168, 0xff800000, v166
	v_exp_f32_e32 v172, v168
	v_sub_f32_e32 v168, v188, v166
	v_exp_f32_e32 v180, v168
	v_sub_f32_e32 v168, v209, v166
	v_exp_f32_e32 v181, v168
	v_sub_f32_e32 v168, v208, v166
	v_exp_f32_e32 v182, v168
	v_sub_f32_e32 v168, v225, v166
	v_add_f32_e32 v222, v165, v167
	v_add_f32_e32 v165, 0, v172
	v_exp_f32_e32 v183, v168
	v_sub_f32_e32 v168, v223, v166
	v_exp_f32_e32 v184, v168
	v_sub_f32_e32 v168, v233, v166
	v_exp_f32_e32 v185, v168
	v_sub_f32_e32 v168, v231, v166
	v_exp_f32_e32 v186, v168
	v_sub_f32_e32 v168, v237, v166
	v_exp_f32_e32 v187, v168
	ds_read2_b64 v[168:171], v162 offset0:128 offset1:130
	ds_read2_b64 v[176:179], v164 offset0:192 offset1:194
	v_sub_f32_e32 v173, v212, v166
	v_cvt_pk_bf16_f32 v172, v172, v172
	v_exp_f32_e32 v188, v173
	v_mov_b32_e32 v173, v172
	v_mov_b32_e32 v174, v172
	v_mov_b32_e32 v175, v172
	v_sub_f32_e32 v167, v189, v166
	v_exp_f32_e32 v167, v167
	s_waitcnt lgkmcnt(1)
	v_sub_f32_e32 v168, v227, v166
	v_exp_f32_e32 v189, v168
	v_sub_f32_e32 v168, v224, v166
	v_exp_f32_e32 v202, v168
	ds_read2_b64 v[168:171], v162 offset0:132 offset1:134
	v_add_f32_e32 v165, v167, v165
	v_add_f32_e32 v165, v180, v165
	s_waitcnt lgkmcnt(1)
	ds_read2_b64 v[176:179], v164 offset0:196 offset1:198
	v_sub_f32_e32 v173, v229, v166
	v_exp_f32_e32 v204, v173
	v_cvt_pk_bf16_f32 v174, v167, v180
	v_cvt_pk_bf16_f32 v175, v181, v182
	v_mov_b32_e32 v173, v172
	v_add_f32_e32 v165, v181, v165
	v_add_f32_e32 v165, v182, v165
	s_waitcnt lgkmcnt(1)
	v_mfma_f32_32x32x16_bf16 v[82:97], v[168:171], v[172:175], v[82:97]
	ds_read2_b64 v[168:171], v162 offset0:136 offset1:138
	v_add_f32_e32 v165, v183, v165
	v_add_f32_e32 v165, v184, v165
	v_add_f32_e32 v165, v185, v165
	v_add_f32_e32 v165, v186, v165
	v_sub_f32_e32 v203, v235, v166
	v_sub_f32_e32 v167, v234, v166
	s_waitcnt lgkmcnt(1)
	v_mfma_f32_32x32x16_bf16 v[66:81], v[176:179], v[172:175], v[66:81]
	ds_read2_b64 v[176:179], v164 offset0:200 offset1:202
	v_sub_f32_e32 v172, v226, v166
	v_exp_f32_e32 v180, v172
	v_cvt_pk_bf16_f32 v172, v183, v184
	v_cvt_pk_bf16_f32 v173, v185, v186
	v_cvt_pk_bf16_f32 v174, v187, v188
	v_cvt_pk_bf16_f32 v175, v189, v202
	v_add_f32_e32 v165, v187, v165
	v_exp_f32_e32 v203, v203
	s_waitcnt lgkmcnt(1)
	v_mfma_f32_32x32x16_bf16 v[82:97], v[168:171], v[172:175], v[82:97]
	v_sub_f32_e32 v168, v230, v166
	v_exp_f32_e32 v181, v168
	v_sub_f32_e32 v168, v228, v166
	v_exp_f32_e32 v182, v168
	v_sub_f32_e32 v168, v236, v166
	v_exp_f32_e32 v183, v168
	ds_read2_b64 v[168:171], v162 offset0:140 offset1:142
	s_waitcnt lgkmcnt(1)
	v_mfma_f32_32x32x16_bf16 v[66:81], v[176:179], v[172:175], v[66:81]
	ds_read2_b64 v[176:179], v164 offset0:204 offset1:206
	v_sub_f32_e32 v162, v232, v166
	v_exp_f32_e32 v167, v167
	v_exp_f32_e32 v162, v162
	v_add_f32_e32 v165, v188, v165
	v_add_f32_e32 v165, v189, v165
	v_add_f32_e32 v165, v202, v165
	v_add_f32_e32 v165, v203, v165
	v_cvt_pk_bf16_f32 v172, v203, v204
	v_cvt_pk_bf16_f32 v173, v167, v180
	v_cvt_pk_bf16_f32 v174, v181, v182
	v_cvt_pk_bf16_f32 v175, v183, v162
	v_add_f32_e32 v165, v204, v165
	v_add_f32_e32 v164, v167, v165
	s_waitcnt lgkmcnt(1)
	v_mfma_f32_32x32x16_bf16 v[82:97], v[168:171], v[172:175], v[82:97]
	v_add_f32_e32 v164, v180, v164
	v_add_f32_e32 v164, v181, v164
	v_add_f32_e32 v164, v182, v164
	v_add_f32_e32 v164, v183, v164
	v_add_f32_e32 v162, v162, v164
	v_add_f32_e32 v162, v238, v162
	s_waitcnt lgkmcnt(0)
	v_mfma_f32_32x32x16_bf16 v[66:81], v[176:179], v[172:175], v[66:81]
.LBB0_434:
	s_or_b64 exec, exec, s[86:87]
	s_mov_b64 s[86:87], 0

.LBB0_439:
	v_sub_f32_e32 v34, v34, v221
	v_exp_f32_e32 v223, v34
	v_sub_f32_e32 v34, v35, v221
	v_exp_f32_e32 v224, v34
	v_sub_f32_e32 v34, v36, v221
	v_exp_f32_e32 v225, v34
	v_sub_f32_e32 v34, v37, v221
	v_exp_f32_e32 v226, v34
	v_sub_f32_e32 v34, v38, v221
	v_exp_f32_e32 v227, v34
	v_sub_f32_e32 v34, v39, v221
	v_exp_f32_e32 v228, v34
	v_sub_f32_e32 v34, v40, v221
	v_exp_f32_e32 v229, v34
	v_sub_f32_e32 v34, v41, v221
	v_exp_f32_e32 v230, v34
	v_sub_f32_e32 v34, v42, v221
	v_exp_f32_e32 v231, v34
	v_sub_f32_e32 v34, v43, v221
	v_exp_f32_e32 v232, v34
	v_sub_f32_e32 v34, v44, v221
	v_exp_f32_e32 v233, v34
	v_sub_f32_e32 v34, v45, v221
	v_exp_f32_e32 v234, v34
	v_sub_f32_e32 v34, v46, v221
	v_exp_f32_e32 v235, v34
	v_sub_f32_e32 v34, v47, v221
	v_exp_f32_e32 v236, v34
	v_sub_f32_e32 v34, v48, v221
	v_exp_f32_e32 v237, v34
	v_sub_f32_e32 v34, v49, v221
	v_exp_f32_e32 v238, v34
	v_sub_f32_e32 v34, v50, v221
	v_exp_f32_e32 v239, v34
	v_sub_f32_e32 v34, v51, v221
	v_exp_f32_e32 v240, v34
	v_sub_f32_e32 v34, v52, v221
	v_exp_f32_e32 v241, v34
	v_sub_f32_e32 v34, v53, v221
	v_exp_f32_e32 v242, v34
	v_sub_f32_e32 v34, v54, v221
	v_exp_f32_e32 v243, v34
	v_sub_f32_e32 v34, v55, v221
	v_exp_f32_e32 v244, v34
	v_sub_f32_e32 v34, v56, v221
	v_lshl_add_u32 v170, s3, 1, v217
	v_exp_f32_e32 v245, v34
	v_sub_f32_e32 v34, v57, v221
	v_exp_f32_e32 v246, v34
	v_sub_f32_e32 v34, v58, v221
	v_add_u32_e32 v38, 0x3000, v170
	v_add_u32_e32 v39, 0x4000, v170
	v_exp_f32_e32 v247, v34
	v_sub_f32_e32 v34, v59, v221
	ds_read2_b64 v[166:169], v38 offset0:128 offset1:130
	ds_read2_b64 v[162:165], v38 offset0:132 offset1:134
	ds_read2_b64 v[170:173], v39 offset0:192 offset1:194
	v_exp_f32_e32 v248, v34
	v_sub_f32_e32 v34, v60, v221
	v_exp_f32_e32 v249, v34
	v_sub_f32_e32 v34, v61, v221
	v_exp_f32_e32 v250, v34
	v_sub_f32_e32 v34, v62, v221
	v_exp_f32_e32 v251, v34
	v_sub_f32_e32 v34, v63, v221
	v_exp_f32_e32 v209, v34
	v_sub_f32_e32 v34, v64, v221
	v_exp_f32_e32 v212, v34
	v_sub_f32_e32 v34, v65, v221
	v_exp_f32_e32 v208, v34
	v_cvt_pk_bf16_f32 v34, v223, v224
	v_cvt_pk_bf16_f32 v35, v225, v226
	v_cvt_pk_bf16_f32 v36, v227, v228
	v_cvt_pk_bf16_f32 v37, v229, v230
	ds_read2_b64 v[174:177], v39 offset0:196 offset1:198
	ds_read2_b64 v[178:181], v38 offset0:136 offset1:138
	s_waitcnt lgkmcnt(4)
	v_mfma_f32_32x32x16_bf16 v[114:129], v[166:169], v[34:37], v[114:129]
	ds_read2_b64 v[182:185], v39 offset0:200 offset1:202
	ds_read2_b64 v[186:189], v38 offset0:140 offset1:142
	v_cvt_pk_bf16_f32 v202, v247, v248
	v_cvt_pk_bf16_f32 v203, v249, v250
	v_cvt_pk_bf16_f32 v204, v251, v209
	v_cvt_pk_bf16_f32 v205, v212, v208
	s_waitcnt lgkmcnt(4)
	v_mfma_f32_32x32x16_bf16 v[98:113], v[170:173], v[34:37], v[98:113]
	v_cvt_pk_bf16_f32 v34, v231, v232
	v_cvt_pk_bf16_f32 v35, v233, v234
	v_cvt_pk_bf16_f32 v36, v235, v236
	v_cvt_pk_bf16_f32 v37, v237, v238
	s_nop 1
	v_mfma_f32_32x32x16_bf16 v[114:129], v[162:165], v[34:37], v[114:129]
	s_waitcnt lgkmcnt(3)
	v_mfma_f32_32x32x16_bf16 v[98:113], v[174:177], v[34:37], v[98:113]
	v_cvt_pk_bf16_f32 v34, v239, v240
	v_cvt_pk_bf16_f32 v35, v241, v242
	v_cvt_pk_bf16_f32 v36, v243, v244
	v_cvt_pk_bf16_f32 v37, v245, v246
	s_waitcnt lgkmcnt(2)
	s_nop 0
	v_mfma_f32_32x32x16_bf16 v[114:129], v[178:181], v[34:37], v[114:129]
	s_waitcnt lgkmcnt(1)
	v_mfma_f32_32x32x16_bf16 v[98:113], v[182:185], v[34:37], v[98:113]
	ds_read2_b64 v[44:47], v39 offset0:204 offset1:206
	v_max_f32_e32 v34, v19, v19
	v_max_f32_e32 v35, v18, v18
	v_max_f32_e32 v34, v35, v34
	v_max3_f32 v34, v34, v20, v21
	v_max3_f32 v34, v34, v22, v23
	v_max3_f32 v34, v34, v24, v25
	v_max3_f32 v34, v34, v26, v27
	v_max3_f32 v34, v34, v28, v29
	v_max3_f32 v34, v34, v30, v31
	v_max3_f32 v34, v34, v32, v33
	v_max3_f32 v34, v34, v2, v3
	v_max3_f32 v34, v34, v4, v5
	v_max3_f32 v34, v34, v6, v7
	v_max3_f32 v34, v34, v8, v9
	v_max3_f32 v34, v34, v10, v11
	v_max3_f32 v34, v34, v12, v13
	v_max3_f32 v34, v34, v14, v15
	v_max3_f32 v34, v34, v16, v17
	s_waitcnt lgkmcnt(1)
	v_mfma_f32_32x32x16_bf16 v[114:129], v[186:189], v[202:205], v[114:129]
	ds_bpermute_b32 v35, v222, v34
	s_waitcnt lgkmcnt(0)
	v_max_f32_e32 v35, v35, v35
	v_max_f32_e32 v34, v34, v35
	v_mfma_f32_32x32x16_bf16 v[98:113], v[44:47], v[202:205], v[98:113]
	v_cmp_gt_f32_e32 vcc, v34, v0
	s_cbranch_vccz .LBB0_441
	v_max_f32_e32 v34, v34, v34
	v_max_f32_e32 v35, v0, v0
	v_max_f32_e32 v34, v35, v34
	v_sub_f32_e32 v0, v0, v34
	v_exp_f32_e32 v0, v0
	s_nop 0
	v_mul_f32_e32 v219, v219, v0
	v_pk_mul_f32 v[96:97], v[96:97], v[0:1] op_sel_hi:[1,0]
	v_pk_mul_f32 v[94:95], v[94:95], v[0:1] op_sel_hi:[1,0]
	v_pk_mul_f32 v[92:93], v[92:93], v[0:1] op_sel_hi:[1,0]
	v_pk_mul_f32 v[90:91], v[90:91], v[0:1] op_sel_hi:[1,0]
	v_pk_mul_f32 v[88:89], v[88:89], v[0:1] op_sel_hi:[1,0]
	v_pk_mul_f32 v[86:87], v[86:87], v[0:1] op_sel_hi:[1,0]
	v_pk_mul_f32 v[84:85], v[84:85], v[0:1] op_sel_hi:[1,0]
	v_pk_mul_f32 v[82:83], v[82:83], v[0:1] op_sel_hi:[1,0]
	v_pk_mul_f32 v[80:81], v[80:81], v[0:1] op_sel_hi:[1,0]
	v_pk_mul_f32 v[78:79], v[78:79], v[0:1] op_sel_hi:[1,0]
	v_pk_mul_f32 v[76:77], v[76:77], v[0:1] op_sel_hi:[1,0]
	v_pk_mul_f32 v[74:75], v[74:75], v[0:1] op_sel_hi:[1,0]
	v_pk_mul_f32 v[72:73], v[72:73], v[0:1] op_sel_hi:[1,0]
	v_pk_mul_f32 v[70:71], v[70:71], v[0:1] op_sel_hi:[1,0]
	v_pk_mul_f32 v[68:69], v[68:69], v[0:1] op_sel_hi:[1,0]
	v_pk_mul_f32 v[66:67], v[66:67], v[0:1] op_sel_hi:[1,0]
	v_mov_b32_e32 v0, v34
.LBB0_441:
	v_add_f32_e32 v34, 0, v223
	v_add_f32_e32 v34, v224, v34
	v_add_f32_e32 v34, v225, v34
	v_add_f32_e32 v34, v226, v34
	v_add_f32_e32 v34, v227, v34
	v_add_f32_e32 v34, v228, v34
	v_add_f32_e32 v34, v229, v34
	v_add_f32_e32 v34, v230, v34
	v_add_f32_e32 v34, v231, v34
	v_add_f32_e32 v34, v232, v34
	v_add_f32_e32 v34, v233, v34
	v_add_f32_e32 v34, v234, v34
	v_add_f32_e32 v34, v235, v34
	v_add_f32_e32 v34, v236, v34
	v_add_f32_e32 v34, v237, v34
	v_add_f32_e32 v34, v238, v34
	v_add_f32_e32 v34, v239, v34
	v_add_f32_e32 v34, v240, v34
	v_add_f32_e32 v34, v241, v34
	v_add_f32_e32 v34, v242, v34
	v_add_f32_e32 v34, v243, v34
	v_add_f32_e32 v34, v244, v34
	v_add_f32_e32 v34, v245, v34
	v_add_f32_e32 v34, v246, v34
	v_add_f32_e32 v34, v247, v34
	v_add_f32_e32 v34, v248, v34
	v_add_f32_e32 v34, v249, v34
	v_add_f32_e32 v34, v250, v34
	v_sub_f32_e32 v18, v18, v0
	v_add_f32_e32 v34, v251, v34
	v_exp_f32_e32 v18, v18
	v_sub_f32_e32 v19, v19, v0
	v_add_f32_e32 v34, v209, v34
	v_exp_f32_e32 v19, v19
	v_sub_f32_e32 v20, v20, v0
	v_add_f32_e32 v34, v212, v34
	v_exp_f32_e32 v20, v20
	v_sub_f32_e32 v21, v21, v0
	v_add_f32_e32 v34, v208, v34
	v_exp_f32_e32 v21, v21
	v_sub_f32_e32 v22, v22, v0
	v_add_f32_e32 v222, v220, v34
	v_add_f32_e32 v34, 0, v18
	v_exp_f32_e32 v22, v22
	v_sub_f32_e32 v23, v23, v0
	v_add_f32_e32 v34, v19, v34
	v_exp_f32_e32 v23, v23
	v_sub_f32_e32 v24, v24, v0
	v_add_f32_e32 v34, v20, v34
	v_exp_f32_e32 v24, v24
	v_sub_f32_e32 v25, v25, v0
	v_add_f32_e32 v34, v21, v34
	v_exp_f32_e32 v25, v25
	v_sub_f32_e32 v26, v26, v0
	v_add_f32_e32 v34, v22, v34
	v_exp_f32_e32 v26, v26
	v_sub_f32_e32 v27, v27, v0
	v_add_f32_e32 v34, v23, v34
	v_exp_f32_e32 v27, v27
	v_sub_f32_e32 v28, v28, v0
	v_add_f32_e32 v34, v24, v34
	v_exp_f32_e32 v28, v28
	v_sub_f32_e32 v29, v29, v0
	v_add_f32_e32 v34, v25, v34
	v_exp_f32_e32 v29, v29
	v_sub_f32_e32 v30, v30, v0
	v_add_f32_e32 v34, v26, v34
	v_exp_f32_e32 v30, v30
	v_sub_f32_e32 v31, v31, v0
	v_add_f32_e32 v34, v27, v34
	v_exp_f32_e32 v31, v31
	v_sub_f32_e32 v32, v32, v0
	v_add_f32_e32 v34, v28, v34
	v_exp_f32_e32 v32, v32
	v_sub_f32_e32 v33, v33, v0
	v_add_f32_e32 v34, v29, v34
	v_exp_f32_e32 v33, v33
	v_sub_f32_e32 v2, v2, v0
	v_add_f32_e32 v34, v30, v34
	v_exp_f32_e32 v35, v2
	v_sub_f32_e32 v2, v3, v0
	v_add_f32_e32 v34, v31, v34
	v_exp_f32_e32 v36, v2
	v_sub_f32_e32 v2, v4, v0
	v_add_f32_e32 v34, v32, v34
	v_exp_f32_e32 v37, v2
	v_sub_f32_e32 v2, v5, v0
	v_add_f32_e32 v34, v33, v34
	v_exp_f32_e32 v38, v2
	v_add_f32_e32 v2, v35, v34
	v_add_f32_e32 v2, v36, v2
	v_add_f32_e32 v2, v37, v2
	v_add_f32_e32 v34, v38, v2
	v_cvt_pk_bf16_f32 v2, v18, v19
	v_cvt_pk_bf16_f32 v3, v20, v21
	v_cvt_pk_bf16_f32 v4, v22, v23
	v_cvt_pk_bf16_f32 v5, v24, v25
	v_sub_f32_e32 v6, v6, v0
	v_exp_f32_e32 v6, v6
	v_mfma_f32_32x32x16_bf16 v[82:97], v[166:169], v[2:5], v[82:97]
	v_sub_f32_e32 v7, v7, v0
	v_exp_f32_e32 v7, v7
	v_sub_f32_e32 v8, v8, v0
	v_exp_f32_e32 v8, v8
	v_add_f32_e32 v18, v6, v34
	v_sub_f32_e32 v9, v9, v0
	v_exp_f32_e32 v9, v9
	v_mfma_f32_32x32x16_bf16 v[66:81], v[170:173], v[2:5], v[66:81]
	v_add_f32_e32 v2, v7, v18
	v_add_f32_e32 v18, v8, v2
	v_cvt_pk_bf16_f32 v2, v26, v27
	v_cvt_pk_bf16_f32 v3, v28, v29
	v_cvt_pk_bf16_f32 v4, v30, v31
	v_cvt_pk_bf16_f32 v5, v32, v33
	v_sub_f32_e32 v10, v10, v0
	v_sub_f32_e32 v11, v11, v0
	v_mfma_f32_32x32x16_bf16 v[82:97], v[162:165], v[2:5], v[82:97]
	v_add_f32_e32 v18, v9, v18
	v_exp_f32_e32 v10, v10
	v_exp_f32_e32 v11, v11
	v_mov_b32_e32 v166, v0
	v_add_f32_e32 v18, v10, v18
	v_add_f32_e32 v18, v11, v18
	v_mfma_f32_32x32x16_bf16 v[66:81], v[174:177], v[2:5], v[66:81]
	v_sub_f32_e32 v2, v12, v0
	v_exp_f32_e32 v12, v2
	v_cvt_pk_bf16_f32 v2, v35, v36
	v_cvt_pk_bf16_f32 v3, v37, v38
	v_cvt_pk_bf16_f32 v4, v6, v7
	v_cvt_pk_bf16_f32 v5, v8, v9
	v_sub_f32_e32 v6, v13, v0
	v_sub_f32_e32 v7, v14, v0
	v_mfma_f32_32x32x16_bf16 v[82:97], v[178:181], v[2:5], v[82:97]
	v_sub_f32_e32 v8, v15, v0
	v_sub_f32_e32 v9, v16, v0
	v_exp_f32_e32 v6, v6
	v_exp_f32_e32 v7, v7
	v_exp_f32_e32 v8, v8
	v_exp_f32_e32 v9, v9
	v_mfma_f32_32x32x16_bf16 v[66:81], v[182:185], v[2:5], v[66:81]
	v_sub_f32_e32 v2, v17, v0
	v_exp_f32_e32 v13, v2
	v_cvt_pk_bf16_f32 v2, v10, v11
	v_cvt_pk_bf16_f32 v3, v12, v6
	v_cvt_pk_bf16_f32 v4, v7, v8
	v_cvt_pk_bf16_f32 v5, v9, v13
	v_add_f32_e32 v10, v12, v18
	v_add_f32_e32 v6, v6, v10
	v_mfma_f32_32x32x16_bf16 v[82:97], v[186:189], v[2:5], v[82:97]
	v_add_f32_e32 v6, v7, v6
	v_add_f32_e32 v6, v8, v6
	v_add_f32_e32 v6, v9, v6
	v_add_f32_e32 v6, v13, v6
	v_add_f32_e32 v162, v219, v6
	v_mfma_f32_32x32x16_bf16 v[66:81], v[44:47], v[2:5], v[66:81]
	s_nop 4

.LBB0_447:
	v_add_u32_e32 v218, 0x7c, v218
	s_andn2_b64 vcc, exec, s[86:87]
	s_add_i32 s84, s84, 64
	s_waitcnt lgkmcnt(0)
	s_barrier
	s_cbranch_vccz .Lnat_exit
	v_mov_b32_e32 v219, v162
	v_mov_b32_e32 v220, v222
	s_mov_b32 s85, s3
	v_mov_b32_e32 v163, v221
	v_mov_b32_e32 v0, v166
	s_branch .LBB0_347
.Lnat_exit:
	v_mov_b64_e32 v[50:51], v[114:115]
	v_mov_b64_e32 v[34:35], v[98:99]
	v_mov_b64_e32 v[18:19], v[82:83]
	v_mov_b64_e32 v[2:3], v[66:67]
	v_mov_b64_e32 v[52:53], v[116:117]
	v_mov_b64_e32 v[54:55], v[118:119]
	v_mov_b64_e32 v[56:57], v[120:121]
	v_mov_b64_e32 v[58:59], v[122:123]
	v_mov_b64_e32 v[60:61], v[124:125]
	v_mov_b64_e32 v[62:63], v[126:127]
	v_mov_b64_e32 v[64:65], v[128:129]
	v_mov_b64_e32 v[36:37], v[100:101]
	v_mov_b64_e32 v[38:39], v[102:103]
	v_mov_b64_e32 v[40:41], v[104:105]
	v_mov_b64_e32 v[42:43], v[106:107]
	v_mov_b64_e32 v[44:45], v[108:109]
	v_mov_b64_e32 v[46:47], v[110:111]
	v_mov_b64_e32 v[48:49], v[112:113]
	v_mov_b64_e32 v[20:21], v[84:85]
	v_mov_b64_e32 v[22:23], v[86:87]
	v_mov_b64_e32 v[24:25], v[88:89]
	v_mov_b64_e32 v[26:27], v[90:91]
	v_mov_b64_e32 v[28:29], v[92:93]
	v_mov_b64_e32 v[30:31], v[94:95]
	v_mov_b64_e32 v[32:33], v[96:97]
	v_mov_b64_e32 v[4:5], v[68:69]
	v_mov_b64_e32 v[6:7], v[70:71]
	v_mov_b64_e32 v[8:9], v[72:73]
	v_mov_b64_e32 v[10:11], v[74:75]
	v_mov_b64_e32 v[12:13], v[76:77]
	v_mov_b64_e32 v[14:15], v[78:79]
	v_mov_b64_e32 v[16:17], v[80:81]
	s_branch .LBB0_319
